# RWKV-7 state scan step A: first two output-tile matrix ops issued after the first eight state conversions so the remaining conversions and decay multiplies run in their shadow (MFMA/VALU interleave)
# speedup vs baseline: 1.0093x; 1.0052x over previous
.LBB0_433:
	s_mul_i32 s1, s0, 37
	s_bfe_u32 s2, s1, 0x80008
	s_lshr_b32 s1, s1, 8
	s_sub_i32 s1, s0, s1
	s_bfe_u32 s1, s1, 0x70001
	s_add_i32 s1, s1, s2
	s_bfe_u32 s1, s1, 0x60002
	s_mul_i32 s1, s1, 7
	s_sub_i32 s1, s0, s1
	s_and_b32 s1, s1, 0xff
	s_mulk_i32 s1, 0x4800
	v_add_u32_e32 v136, s1, v151
	ds_read_b128 v[228:231], v136 offset:17792
	ds_read_b128 v[232:235], v136 offset:17824
	ds_read_b128 v[236:239], v136 offset:17856
	ds_read_b128 v[240:243], v136 offset:17888
	ds_read_b128 v[128:131], v136 offset:17920
	ds_read_b128 v[132:135], v136 offset:17952
	ds_read_b128 v[220:223], v136 offset:17984
	ds_read_b128 v[224:227], v136 offset:18016
	v_cvt_pk_bf16_f32 v112, v16, v17
	v_cvt_pk_bf16_f32 v113, v18, v19
	v_cvt_pk_bf16_f32 v114, v20, v21
	v_cvt_pk_bf16_f32 v115, v22, v23
	v_cvt_pk_bf16_f32 v116, v24, v25
	v_cvt_pk_bf16_f32 v117, v26, v27
	v_cvt_pk_bf16_f32 v118, v28, v29
	v_cvt_pk_bf16_f32 v119, v30, v31
	s_nop 1
	v_mfma_f32_32x32x16_bf16 v[32:47], v[48:51], v[112:115], 0
	v_mfma_f32_32x32x16_bf16 v[32:47], v[52:55], v[116:119], v[32:47]
	v_cvt_pk_bf16_f32 v120, v0, v1
	v_cvt_pk_bf16_f32 v121, v2, v3
	v_cvt_pk_bf16_f32 v122, v4, v5
	v_cvt_pk_bf16_f32 v123, v6, v7
	v_cvt_pk_bf16_f32 v124, v8, v9
	v_cvt_pk_bf16_f32 v125, v10, v11
	v_cvt_pk_bf16_f32 v126, v12, v13
	v_cvt_pk_bf16_f32 v127, v14, v15
	s_waitcnt lgkmcnt(0)
	v_pk_mul_f32 v[16:17], v[16:17], v[228:229]
	v_pk_mul_f32 v[18:19], v[18:19], v[230:231]
	v_pk_mul_f32 v[20:21], v[20:21], v[232:233]
	v_pk_mul_f32 v[22:23], v[22:23], v[234:235]
	v_pk_mul_f32 v[24:25], v[24:25], v[236:237]
	v_pk_mul_f32 v[26:27], v[26:27], v[238:239]
	v_pk_mul_f32 v[28:29], v[28:29], v[240:241]
	v_pk_mul_f32 v[30:31], v[30:31], v[242:243]
	v_mul_f32_e64 v0, v0, v128
	v_mul_f32_e64 v1, v1, v129
	v_mul_f32_e64 v2, v2, v130
	v_mul_f32_e64 v3, v3, v131
	v_mul_f32_e64 v4, v4, v132
	v_mul_f32_e64 v5, v5, v133
	v_pk_mul_f32 v[6:7], v[6:7], v[134:135]
	s_or_b32 s1, s0, 1
	v_mfma_f32_32x32x16_bf16 v[16:31], v[72:75], v[112:115], v[16:31]
	s_and_b32 s2, s1, 0xff
	v_mul_f32_e64 v8, v8, v220
	v_mul_f32_e64 v9, v9, v221
	v_mul_f32_e64 v10, v10, v222
	v_mul_f32_e64 v11, v11, v223
	v_pk_mul_f32 v[12:13], v[12:13], v[224:225]
	v_pk_mul_f32 v[14:15], v[14:15], v[226:227]
	s_mul_i32 s2, s2, 37
	s_lshr_b32 s2, s2, 8
	s_sub_i32 s3, s1, s2
	s_bfe_u32 s3, s3, 0x70001
	s_add_i32 s3, s3, s2
	s_lshr_b32 s2, s3, 2
	s_mul_i32 s2, s2, 7
	s_sub_i32 s1, s1, s2
	s_and_b32 s1, s1, 0xff
	v_mfma_f32_32x32x16_bf16 v[0:15], v[88:91], v[112:115], v[0:15]
	s_mulk_i32 s1, 0x4800
	s_add_i32 s1, s1, 0
	v_add_u32_e32 v192, s1, v144
	v_add_u32_e32 v180, v192, v156
	s_cmpk_gt_u32 s0, 0x7d
	s_cselect_b64 s[2:3], -1, 0
	v_mfma_f32_32x32x16_bf16 v[16:31], v[76:79], v[116:119], v[16:31]
	s_and_b64 vcc, exec, s[2:3]
	v_mfma_f32_32x32x16_bf16 v[32:47], v[56:59], v[120:123], v[32:47]
	v_mfma_f32_32x32x16_bf16 v[0:15], v[92:95], v[116:119], v[0:15]
	v_mfma_f32_32x32x16_bf16 v[16:31], v[80:83], v[120:123], v[16:31]
	v_mfma_f32_32x32x16_bf16 v[32:47], v[60:63], v[124:127], v[32:47]
	v_mfma_f32_32x32x16_bf16 v[0:15], v[96:99], v[120:123], v[0:15]
	v_mfma_f32_32x32x16_bf16 v[16:31], v[84:87], v[124:127], v[16:31]
	v_mfma_f32_32x32x16_bf16 v[32:47], v[68:71], v[64:67], v[32:47]
	v_mfma_f32_32x32x16_bf16 v[0:15], v[100:103], v[124:127], v[0:15]
	s_nop 10
	v_add_u32_e32 v45, s1, v153
	v_add_u32_e32 v46, v45, v152
	v_add_u32_e32 v160, v45, v155
	v_add_u32_e32 v44, v192, v150
	ds_read2_b64 v[40:43], v46 offset1:2
	ds_read2_b64 v[116:119], v46 offset0:4 offset1:6
	ds_read2_b64 v[120:123], v46 offset0:8 offset1:10
	ds_read2_b64 v[124:127], v46 offset0:12 offset1:14
	v_add_u32_e32 v46, v192, v154
	v_add_u32_e32 v132, 0x800, v160
	v_mfma_f32_32x32x16_bf16 v[16:31], v[104:107], v[64:67], v[16:31]
	v_add_u32_e32 v172, 0x1800, v160
	ds_read_b128 v[112:115], v44 offset:14720
	ds_read_b128 v[128:131], v46 offset:2176
	ds_read2_b64 v[44:47], v132 offset0:112 offset1:114
	ds_read2_b64 v[140:143], v132 offset0:116 offset1:118
	ds_read2_b64 v[136:139], v132 offset0:120 offset1:122
	ds_read2_b64 v[132:135], v132 offset0:124 offset1:126
	ds_read2_b64 v[160:163], v172 offset0:144 offset1:146
	ds_read2_b64 v[164:167], v172 offset0:148 offset1:150
	ds_read2_b64 v[168:171], v172 offset0:152 offset1:154
	ds_read2_b64 v[172:175], v172 offset0:156 offset1:158
	ds_read_b128 v[176:179], v180 offset:11648
	ds_read_b128 v[180:183], v180 offset:13184
	ds_read_b128 v[220:223], v192 offset:17888
	ds_read_b128 v[224:227], v192 offset:17856
	ds_read_b128 v[228:231], v192 offset:17824
	ds_read_b128 v[232:235], v192 offset:17792
	ds_read_b128 v[236:239], v192 offset:18016
	ds_read_b128 v[240:243], v192 offset:17984
	ds_read_b128 v[244:247], v192 offset:17952
	ds_write2st64_b32 v158, v32, v33 offset1:1
	ds_write2st64_b32 v158, v34, v35 offset0:2 offset1:3
	ds_write2st64_b32 v158, v36, v37 offset0:8 offset1:9
	ds_write2st64_b32 v158, v38, v39 offset0:10 offset1:11
	s_waitcnt lgkmcnt(0)
	s_barrier
	ds_read_b128 v[36:39], v192 offset:17920
	v_cvt_pk_bf16_f32 v32, v16, v17
	v_mfma_f32_32x32x16_bf16 v[0:15], v[108:111], v[64:67], v[0:15]
	v_cvt_pk_bf16_f32 v33, v18, v19
	v_cvt_pk_bf16_f32 v34, v20, v21
	v_cvt_pk_bf16_f32 v35, v22, v23
	v_cvt_pk_bf16_f32 v184, v24, v25
	v_cvt_pk_bf16_f32 v185, v26, v27
	v_cvt_pk_bf16_f32 v186, v28, v29
	v_cvt_pk_bf16_f32 v187, v30, v31
	v_cvt_pk_bf16_f32 v188, v0, v1
	v_cvt_pk_bf16_f32 v189, v2, v3
	v_cvt_pk_bf16_f32 v190, v4, v5
	v_cvt_pk_bf16_f32 v191, v6, v7
	v_cvt_pk_bf16_f32 v216, v8, v9
	v_cvt_pk_bf16_f32 v217, v10, v11
	v_cvt_pk_bf16_f32 v218, v12, v13
	v_cvt_pk_bf16_f32 v219, v14, v15
	v_pk_mul_f32 v[28:29], v[28:29], v[220:221]
	v_pk_mul_f32 v[30:31], v[30:31], v[222:223]
	v_pk_mul_f32 v[24:25], v[24:25], v[224:225]
	v_pk_mul_f32 v[26:27], v[26:27], v[226:227]
	v_pk_mul_f32 v[20:21], v[20:21], v[228:229]
	v_pk_mul_f32 v[22:23], v[22:23], v[230:231]
	v_pk_mul_f32 v[18:19], v[18:19], v[234:235]
	v_pk_mul_f32 v[16:17], v[16:17], v[232:233]
	v_pk_mul_f32 v[12:13], v[12:13], v[236:237]
	v_pk_mul_f32 v[14:15], v[14:15], v[238:239]
	v_mfma_f32_32x32x16_bf16 v[16:31], v[44:47], v[32:35], v[16:31]
	v_mul_f32_e64 v8, v8, v240
	v_mul_f32_e64 v9, v9, v241
	v_mul_f32_e64 v10, v10, v242
	v_mul_f32_e64 v11, v11, v243
	v_pk_mul_f32 v[4:5], v[4:5], v[244:245]
	v_pk_mul_f32 v[6:7], v[6:7], v[246:247]
	v_mfma_f32_32x32x16_bf16 v[16:31], v[140:143], v[184:187], v[16:31]
	s_waitcnt lgkmcnt(0)
	v_mul_f32_e64 v2, v2, v38
	v_mul_f32_e64 v3, v3, v39
	v_mul_f32_e64 v0, v0, v36
	v_mul_f32_e64 v1, v1, v37
	s_nop 1
	v_mfma_f32_32x32x16_bf16 v[0:15], v[160:163], v[32:35], v[0:15]
	v_mfma_f32_32x32x16_bf16 v[32:47], v[40:43], v[32:35], 0
	v_mfma_f32_32x32x16_bf16 v[32:47], v[116:119], v[184:187], v[32:47]
	v_mfma_f32_32x32x16_bf16 v[0:15], v[164:167], v[184:187], v[0:15]
	v_mfma_f32_32x32x16_bf16 v[32:47], v[120:123], v[188:191], v[32:47]
	v_mfma_f32_32x32x16_bf16 v[16:31], v[136:139], v[188:191], v[16:31]
	v_mfma_f32_32x32x16_bf16 v[0:15], v[168:171], v[188:191], v[0:15]
	v_mfma_f32_32x32x16_bf16 v[32:47], v[124:127], v[216:219], v[32:47]
	v_mfma_f32_32x32x16_bf16 v[16:31], v[132:135], v[216:219], v[16:31]
	v_mfma_f32_32x32x16_bf16 v[0:15], v[172:175], v[216:219], v[0:15]
	v_mfma_f32_32x32x16_bf16 v[32:47], v[128:131], v[112:115], v[32:47]
	v_mfma_f32_32x32x16_bf16 v[16:31], v[176:179], v[112:115], v[16:31]
	v_mfma_f32_32x32x16_bf16 v[0:15], v[180:183], v[112:115], v[0:15]
	s_cbranch_vccnz .LBB0_432
	s_add_i32 s1, s0, 2
	s_and_b32 s4, s1, 0xff
	s_mul_i32 s4, s4, 37
	s_lshr_b32 s5, s4, 8
	s_sub_i32 s5, s1, s5
	s_bfe_u32 s5, s5, 0x70001
	s_bfe_u32 s4, s4, 0x80008
	s_add_i32 s5, s5, s4
	s_bfe_u32 s4, s5, 0x60002
	s_mul_i32 s4, s4, 7
	s_sub_i32 s1, s1, s4
	s_and_b32 s1, s1, 0xff
	s_mulk_i32 s1, 0x4800
	s_add_i32 s1, s1, 0
	v_add_u32_e32 v40, s1, v144
	v_add_u32_e32 v42, s1, v153
	v_add_u32_e32 v41, v40, v150
	v_add_u32_e32 v43, v42, v152
	ds_read2_b64 v[48:51], v43 offset1:2
	ds_read2_b64 v[52:55], v43 offset0:4 offset1:6
	ds_read2_b64 v[56:59], v43 offset0:8 offset1:10
	ds_read2_b64 v[60:63], v43 offset0:12 offset1:14
	v_add_u32_e32 v43, v40, v154
	ds_read_b128 v[64:67], v41 offset:14720
	ds_read_b128 v[68:71], v43 offset:2176
	v_add_u32_e32 v41, v42, v155
	v_add_u32_e32 v42, 0x800, v41
	v_add_u32_e32 v41, 0x1800, v41
	ds_read2_b64 v[72:75], v42 offset0:112 offset1:114
	ds_read2_b64 v[76:79], v42 offset0:116 offset1:118
	ds_read2_b64 v[80:83], v42 offset0:120 offset1:122
	ds_read2_b64 v[84:87], v42 offset0:124 offset1:126
	v_add_u32_e32 v40, v40, v156
	ds_read2_b64 v[88:91], v41 offset0:144 offset1:146
	ds_read2_b64 v[92:95], v41 offset0:148 offset1:150
	ds_read2_b64 v[96:99], v41 offset0:152 offset1:154
	ds_read2_b64 v[100:103], v41 offset0:156 offset1:158
	ds_read_b128 v[104:107], v40 offset:11648
	ds_read_b128 v[108:111], v40 offset:13184
	s_branch .LBB0_432
